# grid barriers: first poll deferred by one sleep (the immediate poll after arrival is wasted for all but the last arriver and adds traffic to the counter line while arrivals are in flight)
# baseline (speedup 1.0000x reference)
.LBB0_7:
	s_or_b64 exec, exec, s[8:9]
	v_mov_b32_e32 v1, 0
	s_sleep 20
	global_load_dword v2, v1, s[6:7] offset:32 sc1
	v_and_b32_e32 v0, 0xffff0000, v0
	s_waitcnt vmcnt(0)
	v_and_b32_e32 v2, 0xffff0000, v2
	v_cmp_eq_u32_e32 vcc, v2, v0
	s_and_b64 exec, exec, vcc
	s_cbranch_execz .LBB0_10
	s_mov_b64 s[8:9], 0
.LBB0_9:
	s_sleep 1
	s_sleep 20
	global_load_dword v2, v1, s[6:7] offset:32 sc1
	s_waitcnt vmcnt(0)
	v_and_b32_e32 v2, 0xffff0000, v2
	v_cmp_ne_u32_e32 vcc, v2, v0
	s_or_b64 s[8:9], vcc, s[8:9]
	s_andn2_b64 exec, exec, s[8:9]
	s_cbranch_execnz .LBB0_9

.LBB0_35:
	s_or_b64 exec, exec, s[8:9]
	v_mov_b32_e32 v0, 0x3c5e1000
	s_sleep 20
	global_load_dword v0, v0, s[52:53] sc1
	s_add_u32 s8, s52, 0x3c5e1000
	s_addc_u32 s9, s53, 0
	s_waitcnt vmcnt(0)
	v_cmp_le_u32_e32 vcc, s2, v0
	s_cbranch_vccnz .LBB0_38
	v_mov_b32_e32 v0, 0

.LBB0_111:
	s_or_b64 exec, exec, s[10:11]
	v_readlane_b32 s12, v254, 50
	v_mov_b32_e32 v0, 0x3c5e1000
	v_readlane_b32 s13, v254, 51
	s_mul_i32 s2, s2, s94
	s_add_u32 s10, s12, 0x3c5e1000
	s_addc_u32 s11, s13, 0
	v_readlane_b32 s14, v254, 52
	v_readlane_b32 s15, v254, 53
	s_sleep 20
	global_load_dword v0, v0, s[12:13] sc1
	s_waitcnt vmcnt(0)
	v_cmp_le_u32_e32 vcc, s2, v0
	s_cbranch_vccnz .LBB0_114
	v_mov_b32_e32 v0, 0

.LBB0_149:
	s_or_b64 exec, exec, s[6:7]
	v_readlane_b32 s8, v254, 50
	v_mov_b32_e32 v0, 0x3c5e1000
	v_readlane_b32 s9, v254, 51
	s_mul_i32 s2, s2, s94
	s_add_u32 s6, s8, 0x3c5e1000
	s_addc_u32 s7, s9, 0
	v_readlane_b32 s10, v254, 52
	v_readlane_b32 s11, v254, 53
	s_sleep 20
	global_load_dword v0, v0, s[8:9] sc1
	s_waitcnt vmcnt(0)
	v_cmp_le_u32_e32 vcc, s2, v0
	s_cbranch_vccnz .LBB0_152
	v_mov_b32_e32 v0, 0

.LBB0_612:
	s_or_b64 exec, exec, s[4:5]
	s_sleep 20
	global_load_dword v1, v0, s[10:11] sc1
	s_min_u32 s3, s3, 32
	s_mul_i32 s3, s3, s94
	s_waitcnt vmcnt(0)
	v_cmp_le_u32_e32 vcc, s3, v1
	s_cbranch_vccnz .LBB0_614

.LBB0_701:
	s_or_b64 exec, exec, s[2:3]
	v_mov_b32_e32 v0, 0
	s_sleep 20
	global_load_dword v1, v0, s[10:11] sc1
	s_mul_i32 s7, s7, s6
	s_waitcnt vmcnt(0)
	v_cmp_le_u32_e32 vcc, s7, v1
	s_cbranch_vccnz .LBB0_703
